# snake MFMA order + merged 64-MFMA-slot K-loops in P8 and P9 (role-split saddr LDS-DMA)
# speedup vs baseline: 1.0722x; 1.0032x over previous
; #define PG8_STAGE(bufoff, gbase, voff) do { _Pragma("unroll") for (int _i = 0; _i < 2; ++_i) \
;         __builtin_amdgcn_global_load_lds((const unsigned*)((const char*)(gbase) + (voff)[_i]), (PG8_LAS unsigned*)(lds + (bufoff) + ldsw + _i * 8192), 16, 0, 0); } while (0)
; #define PG8_WAIT_V(n) asm volatile("s_waitcnt vmcnt(" #n ")" ::: "memory")
; #define PG8_BAR __builtin_amdgcn_s_barrier()
; template <class Epi, class Sched, bool ALIGN_EPI>
; __device__ __forceinline__ void gemm_phase(PG8_LAS unsigned char* lds, const Gemm g, const Sched& S, const Epi& E) {
;     ...
;     for (int i = 0; i < 2; ++i) { int R, C; stage_rc(tid * 16 + i * 8192, R, C); const int Rb = Epi::PERM ? ((R & ~31) + perm32(R & 31)) : R;
;         voffA[i] = g.ablk ? (unsigned)((C >> 4) * g.ablk + R * 16 + (C & 15)) * 2u : (unsigned)(R * g.lda + C) * 2u; voffB[i] = (unsigned)(Rb * g.ldb + C) * 2u; }
;     const size_t kstep = (size_t)(BK * 2), kstepA = g.ablk ? (size_t)4 * g.ablk * 2 : kstep;
;     const size_t hstepA = g.ablk ? (size_t)HALF * 16 * 2 : (size_t)HALF * g.lda * 2, hstepB = (size_t)HALF * g.ldb * 2;
;     const size_t tstepA = 2 * hstepA, tstepB = 2 * hstepB;
;     const unsigned ldsw = (unsigned)wid * 1024u;
;     const size_t tailoff = (size_t)(nt - 2) * (size_t)(BK * 2), tailoffA = (size_t)(nt - 2) * kstepA;
;     const int aoff = lds_byte(wr * 64 + fr, fq * 8), boff = lds_byte(wc * 32 + fr, fq * 8);
;     ...
;     PG8_STAGE(PG8_SB(0, 0), cB, voffB); PG8_STAGE(PG8_SB(0, 1), cB + hstepB, voffB); PG8_STAGE(PG8_SA(0, 0), cA, voffA); PG8_STAGE(PG8_SA(0, 1), cA + hstepA, voffA);
;     if (wr == 1) PG8_BAR;
;     PG8_WAIT_V(2); PG8_BAR;
;     PG8_STAGE(PG8_SB(1, 0), cB + kstep, voffB); PG8_STAGE(PG8_SA(1, 0), cA + kstepA, voffA); PG8_STAGE(PG8_SB(1, 1), cB + hstepB + kstep, voffB);
;     PG8_WAIT_V(6); PG8_BAR;
.LBB0_934:
	s_lshl_b32 s1, s1, 5
	s_mov_b64 s[12:13], 0x80
	s_and_b32 s1, s1, 0x60
	s_add_i32 m0, s37, 0x18000
	v_lshl_add_u64 v[8:9], v[8:9], 0, s[12:13]
	s_lshl_b32 s2, s7, 13
	s_lshl_b32 s15, s1, 7
	s_waitcnt vmcnt(0)
	s_barrier
	global_load_lds_dwordx4 v[8:9], off
	v_lshl_add_u64 v[4:5], v[4:5], 0, s[12:13]
	s_add_i32 m0, s37, 0x1a000
	s_add_i32 s43, s37, 0x8000
	s_add_i32 s44, s37, 0xa000
	global_load_lds_dwordx4 v[4:5], off
	v_lshl_add_u64 v[2:3], v[2:3], 0, s[12:13]
	s_mov_b32 m0, s43
	s_add_u32 s18, s28, 0x160080
	global_load_lds_dwordx4 v[2:3], off
	v_lshl_add_u64 v[2:3], v[6:7], 0, s[12:13]
	s_mov_b32 m0, s44
	s_addc_u32 s19, s29, 0
	global_load_lds_dwordx4 v[2:3], off
	s_add_i32 m0, s37, 0x1c000
	v_lshl_add_u64 v[2:3], s[18:19], 0, v[132:133]
	global_load_lds_dwordx4 v[2:3], off
	v_lshl_add_u64 v[2:3], s[18:19], 0, v[136:137]
	s_add_i32 m0, s37, 0x1e000
	s_cmpk_lt_u32 s6, 0x100
	global_load_lds_dwordx4 v[2:3], off
	v_lshrrev_b32_e32 v3, 1, v10
	v_and_b32_e32 v3, 24, v3
	v_and_b32_e32 v2, 15, v10
	v_lshlrev_b32_e32 v4, 1, v3
	v_lshl_or_b32 v1, s7, 6, v2
	v_lshl_or_b32 v2, v2, 6, v4
	v_lshlrev_b32_e32 v4, 2, v10
	v_and_b32_e32 v4, 32, v4
	v_bitop3_b32 v5, v2, s2, v4 bitop3:0xde
	v_bitop3_b32 v153, v2, s15, v4 bitop3:0xde
	v_or_b32_e32 v154, s1, v3
	v_lshrrev_b32_e32 v3, 1, v11
	v_mul_lo_u32 v2, v12, s0
	v_mad_u64_u32 v[2:3], s[6:7], v3, s16, v[2:3]
	v_or_b32_e32 v2, v2, v13
	s_mov_b64 s[18:19], 0x160080
	v_add_lshl_u32 v2, v2, v14, 1
	v_mov_b32_e32 v3, v133
	v_lshl_add_u64 v[138:139], v[2:3], 0, s[18:19]
	v_lshrrev_b32_e32 v3, 1, v15
	v_mul_lo_u32 v2, v16, s0
	v_mad_u64_u32 v[2:3], s[0:1], v3, s16, v[2:3]
	s_waitcnt vmcnt(6)
	v_or_b32_e32 v2, v2, v17
	s_sext_i32_i8 s56, s14
	s_cselect_b64 s[14:15], -1, 0
	v_add_lshl_u32 v2, v2, v18, 1
	v_mov_b32_e32 v3, v133
	s_add_i32 s47, 0, 0x10000
	s_add_i32 s48, 0, 0x14000
	s_ashr_i32 s45, s33, 31
	v_lshl_add_u64 v[140:141], v[2:3], 0, s[18:19]
	v_mov_b64_e32 v[142:143], 0x200
	v_mov_b64_e32 v[144:145], 0x1ff
	v_add_u32_e32 v155, s47, v153
	v_add_u32_e32 v156, s48, v153
	v_add_u32_e32 v157, 0, v5
	s_mov_b64 s[16:17], 0x80000
	s_mov_b32 s49, 0x80000
	s_mov_b64 s[18:19], 0x90000
	s_mov_b32 s50, 0x90000
	s_mov_b64 s[20:21], 0xa0000
	s_mov_b32 s51, 0xa0000
	s_mov_b64 s[22:23], 0xb0000
	s_mov_b32 s52, 0xb0000
	s_add_u32 s58, s26, 0x160080
	s_addc_u32 s59, s27, 0
	s_add_i32 m0, s37, 0xc000
	s_nop 0
	global_load_lds_dwordx4 v130, s[58:59]
	s_barrier
	s_branch .LBB0_937

; #define PG8_STAGE(bufoff, gbase, voff) do { _Pragma("unroll") for (int _i = 0; _i < 2; ++_i) \
;         __builtin_amdgcn_global_load_lds((const unsigned*)((const char*)(gbase) + (voff)[_i]), (PG8_LAS unsigned*)(lds + (bufoff) + ldsw + _i * 8192), 16, 0, 0); } while (0)
; #define PG8_LDA(dst, b, h) do { _Pragma("unroll") for (int m = 0; m < 4; ++m) _Pragma("unroll") for (int k = 0; k < 2; ++k) dst[m][k] = *(const PG8_LAS bf16x8*)(lds + PG8_SA(b, h) + aoff + m * 2048 + k * 1024); } while (0)
; #define PG8_LDB(dst, b, h) do { _Pragma("unroll") for (int n = 0; n < 2; ++n) _Pragma("unroll") for (int k = 0; k < 2; ++k) dst[n][k] = *(const PG8_LAS bf16x8*)(lds + PG8_SB(b, h) + boff + n * 2048 + k * 1024); } while (0)
; #define PG8_MMA(ai, bj, At, Bt) do { __builtin_amdgcn_s_setprio(1); _Pragma("unroll") for (int m = 0; m < 4; ++m) _Pragma("unroll") for (int n = 0; n < 2; ++n) _Pragma("unroll") for (int k = 0; k < 2; ++k) \
;         acc[ai][bj][m][n] = __builtin_amdgcn_mfma_f32_16x16x32_bf16(Bt[n][k], At[m][k], acc[ai][bj][m][n], 0, 0, 0); __builtin_amdgcn_s_setprio(0); } while (0)
; #define PG8_WAIT_V(n) asm volatile("s_waitcnt vmcnt(" #n ")" ::: "memory")
; template <class Epi, class Sched, bool ALIGN_EPI>
; __device__ __forceinline__ void gemm_phase(PG8_LAS unsigned char* lds, const Gemm g, const Sched& S, const Epi& E) {
;     ...
;         for (int t = 0; t < nt; t += 2) {
;             if constexpr (Epi::MIDK) { if (t == (nt >> 1)) E.midk(acc, cur, wr, fr); }
;             const bool last = (t == nt - 2);
;             const char* a1 = cA + (size_t)(t + 1) * kstepA;
;             const char* a2 = last ? nA : cA + (size_t)(t + 2) * kstepA; const char* b2 = last ? nB : cB + (size_t)(t + 2) * kstep;
;             const char* a3 = a2 + kstepA; const char* b3 = b2 + kstep;
;             PG8_LDB(B0, 0, 0); PG8_LDB(B1, 0, 1); PG8_SCHED; PG8_LDA(At, 0, 0); PG8_STAGE(PG8_SA(1, 1), a1 + hstepA, voffA);
;             PG8_WAIT_V(8); PG8_WAIT_L(0); PG8_BAR; PG8_MMA(0, 0, At, B0); PG8_MMA(0, 1, At, B1); PG8_BAR; PG8_SCHED;
;     ...
; #pragma unroll
;         for (int a = 0; a < 2; ++a)
; #pragma unroll
;             for (int b = 0; b < 2; ++b)
; #pragma unroll
;                 for (int m = 0; m < 4; ++m)
; #pragma unroll
;                     for (int n = 0; n < 2; ++n) acc[a][b][m][n] = (f32x4){0.f, 0.f, 0.f, 0.f};
;         cur = nxt; cA = nA; cB = nB; ++ui;
.LBB0_947:
	s_add_u32 s6, s6, s30
	s_addc_u32 s7, s7, s31
	s_add_u32 s24, s34, s24
	s_addc_u32 s25, s35, s25
	s_add_u32 s57, s28, 0x100
	v_mov_b32_e32 v2, 0
	s_addc_u32 s58, s29, 0
	s_mov_b32 s59, -2
	v_mov_b32_e32 v3, v2
	v_mov_b32_e32 v4, v2
	v_mov_b32_e32 v5, v2
	v_mov_b32_e32 v6, v2
	v_mov_b32_e32 v7, v2
	v_mov_b32_e32 v8, v2
	v_mov_b32_e32 v9, v2
	v_mov_b32_e32 v10, v2
	v_mov_b32_e32 v11, v2
	v_mov_b32_e32 v12, v2
	v_mov_b32_e32 v13, v2
	v_mov_b32_e32 v18, v2
	v_mov_b32_e32 v19, v2
	v_mov_b32_e32 v20, v2
	v_mov_b32_e32 v21, v2
	v_mov_b32_e32 v26, v2
	v_mov_b32_e32 v27, v2
	v_mov_b32_e32 v28, v2
	v_mov_b32_e32 v29, v2
	v_mov_b32_e32 v34, v2
	v_mov_b32_e32 v35, v2
	v_mov_b32_e32 v36, v2
	v_mov_b32_e32 v37, v2
	v_mov_b32_e32 v42, v2
	v_mov_b32_e32 v43, v2
	v_mov_b32_e32 v44, v2
	v_mov_b32_e32 v45, v2
	v_mov_b32_e32 v50, v2
	v_mov_b32_e32 v51, v2
	v_mov_b32_e32 v52, v2
	v_mov_b32_e32 v53, v2
	v_mov_b32_e32 v14, v2
	v_mov_b32_e32 v15, v2
	v_mov_b32_e32 v16, v2
	v_mov_b32_e32 v17, v2
	v_mov_b32_e32 v22, v2
	v_mov_b32_e32 v23, v2
	v_mov_b32_e32 v24, v2
	v_mov_b32_e32 v25, v2
	v_mov_b32_e32 v30, v2
	v_mov_b32_e32 v31, v2
	v_mov_b32_e32 v32, v2
	v_mov_b32_e32 v33, v2
	v_mov_b32_e32 v38, v2
	v_mov_b32_e32 v39, v2
	v_mov_b32_e32 v40, v2
	v_mov_b32_e32 v41, v2
	v_mov_b32_e32 v46, v2
	v_mov_b32_e32 v47, v2
	v_mov_b32_e32 v48, v2
	v_mov_b32_e32 v49, v2
	v_mov_b32_e32 v54, v2
	v_mov_b32_e32 v55, v2
	v_mov_b32_e32 v56, v2
	v_mov_b32_e32 v57, v2
	v_mov_b32_e32 v58, v2
	v_mov_b32_e32 v59, v2
	v_mov_b32_e32 v60, v2
	v_mov_b32_e32 v61, v2
	v_mov_b32_e32 v62, v2
	v_mov_b32_e32 v63, v2
	v_mov_b32_e32 v64, v2
	v_mov_b32_e32 v65, v2
	v_mov_b32_e32 v66, v2
	v_mov_b32_e32 v67, v2
	v_mov_b32_e32 v68, v2
	v_mov_b32_e32 v69, v2
	v_mov_b32_e32 v70, v2
	v_mov_b32_e32 v71, v2
	v_mov_b32_e32 v72, v2
	v_mov_b32_e32 v73, v2
	v_mov_b32_e32 v74, v2
	v_mov_b32_e32 v75, v2
	v_mov_b32_e32 v76, v2
	v_mov_b32_e32 v77, v2
	v_mov_b32_e32 v82, v2
	v_mov_b32_e32 v83, v2
	v_mov_b32_e32 v84, v2
	v_mov_b32_e32 v85, v2
	v_mov_b32_e32 v90, v2
	v_mov_b32_e32 v91, v2
	v_mov_b32_e32 v92, v2
	v_mov_b32_e32 v93, v2
	v_mov_b32_e32 v98, v2
	v_mov_b32_e32 v99, v2
	v_mov_b32_e32 v100, v2
	v_mov_b32_e32 v101, v2
	v_mov_b32_e32 v106, v2
	v_mov_b32_e32 v107, v2
	v_mov_b32_e32 v108, v2
	v_mov_b32_e32 v109, v2
	v_mov_b32_e32 v114, v2
	v_mov_b32_e32 v115, v2
	v_mov_b32_e32 v116, v2
	v_mov_b32_e32 v117, v2
	v_mov_b32_e32 v78, v2
	v_mov_b32_e32 v79, v2
	v_mov_b32_e32 v80, v2
	v_mov_b32_e32 v81, v2
	v_mov_b32_e32 v86, v2
	v_mov_b32_e32 v87, v2
	v_mov_b32_e32 v88, v2
	v_mov_b32_e32 v89, v2
	v_mov_b32_e32 v94, v2
	v_mov_b32_e32 v95, v2
	v_mov_b32_e32 v96, v2
	v_mov_b32_e32 v97, v2
	v_mov_b32_e32 v102, v2
	v_mov_b32_e32 v103, v2
	v_mov_b32_e32 v104, v2
	v_mov_b32_e32 v105, v2
	v_mov_b32_e32 v110, v2
	v_mov_b32_e32 v111, v2
	v_mov_b32_e32 v112, v2
	v_mov_b32_e32 v113, v2
	v_mov_b32_e32 v118, v2
	v_mov_b32_e32 v119, v2
	v_mov_b32_e32 v120, v2
	v_mov_b32_e32 v121, v2
	v_mov_b32_e32 v122, v2
	v_mov_b32_e32 v123, v2
	v_mov_b32_e32 v124, v2
	v_mov_b32_e32 v125, v2
	v_mov_b32_e32 v126, v2
	v_mov_b32_e32 v127, v2
	v_mov_b32_e32 v128, v2
	v_mov_b32_e32 v129, v2
	s_and_b32 s60, s37, 0xfff
	s_mov_b32 s57, 0
	s_cmp_lt_u32 s37, 0x1000
	s_cbranch_scc0 .Lp9k_B_init
	s_add_u32 s28, s28, 0x80
	s_addc_u32 s29, s29, 0
	s_mov_b64 s[58:59], s[24:25]
.Lp9k_A_loop:
	s_add_i32 m0, s60, 0x18000
	s_nop 0
	global_load_lds_dwordx4 v132, s[28:29]
	s_add_i32 m0, s60, 0x1a000
	s_nop 0
	global_load_lds_dwordx4 v136, s[28:29]
	s_add_u32 s30, s28, 0x58000
	s_addc_u32 s31, s29, 0
	s_add_i32 m0, s60, 0x19000
	s_nop 0
	global_load_lds_dwordx4 v132, s[30:31]
	s_add_i32 m0, s60, 0x1b000
	s_nop 0
	global_load_lds_dwordx4 v136, s[30:31]
	s_add_u32 s30, s28, 0x160000
	s_addc_u32 s31, s29, 0
	s_add_i32 m0, s60, 0x1c000
	s_nop 0
	global_load_lds_dwordx4 v132, s[30:31]
	s_add_i32 m0, s60, 0x1e000
	s_nop 0
	global_load_lds_dwordx4 v136, s[30:31]
	s_add_u32 s30, s28, 0x1b8000
	s_addc_u32 s31, s29, 0
	s_add_i32 m0, s60, 0x1d000
	s_nop 0
	global_load_lds_dwordx4 v132, s[30:31]
	s_add_i32 m0, s60, 0x1f000
	s_nop 0
	global_load_lds_dwordx4 v136, s[30:31]
	s_add_u32 s28, s28, 0x80
	s_addc_u32 s29, s29, 0
	ds_read_b128 v[194:197], v157 offset:0
	ds_read_b128 v[198:201], v157 offset:1024
	ds_read_b128 v[202:205], v157 offset:2048
	ds_read_b128 v[206:209], v157 offset:3072
	ds_read_b128 v[210:213], v157 offset:4096
	ds_read_b128 v[214:217], v157 offset:5120
	ds_read_b128 v[218:221], v157 offset:6144
	ds_read_b128 v[222:225], v157 offset:7168
	ds_read_b128 v[158:161], v155 offset:0
	ds_read_b128 v[162:165], v155 offset:1024
	ds_read_b128 v[166:169], v155 offset:2048
	ds_read_b128 v[174:177], v155 offset:3072
	ds_read_b128 v[178:181], v155 offset:16384
	ds_read_b128 v[182:185], v155 offset:17408
	ds_read_b128 v[186:189], v155 offset:18432
	ds_read_b128 v[190:193], v155 offset:19456
	ds_read_b128 v[226:229], v157 offset:16384
	ds_read_b128 v[230:233], v157 offset:17408
	ds_read_b128 v[234:237], v157 offset:18432
	ds_read_b128 v[238:241], v157 offset:19456
	ds_read_b128 v[242:245], v157 offset:20480
	ds_read_b128 v[246:249], v157 offset:21504
	ds_read_b128 v[250:253], v157 offset:22528
	ds_read_b128 v[142:145], v157 offset:23552
	s_waitcnt vmcnt(8) lgkmcnt(0)
	s_barrier
; #define PG8_STAGE(bufoff, gbase, voff) do { _Pragma("unroll") for (int _i = 0; _i < 2; ++_i) \
;         __builtin_amdgcn_global_load_lds((const unsigned*)((const char*)(gbase) + (voff)[_i]), (PG8_LAS unsigned*)(lds + (bufoff) + ldsw + _i * 8192), 16, 0, 0); } while (0)
; #define PG8_LDA(dst, b, h) do { _Pragma("unroll") for (int m = 0; m < 4; ++m) _Pragma("unroll") for (int k = 0; k < 2; ++k) dst[m][k] = *(const PG8_LAS bf16x8*)(lds + PG8_SA(b, h) + aoff + m * 2048 + k * 1024); } while (0)
; #define PG8_LDB(dst, b, h) do { _Pragma("unroll") for (int n = 0; n < 2; ++n) _Pragma("unroll") for (int k = 0; k < 2; ++k) dst[n][k] = *(const PG8_LAS bf16x8*)(lds + PG8_SB(b, h) + boff + n * 2048 + k * 1024); } while (0)
; #define PG8_MMA(ai, bj, At, Bt) do { __builtin_amdgcn_s_setprio(1); _Pragma("unroll") for (int m = 0; m < 4; ++m) _Pragma("unroll") for (int n = 0; n < 2; ++n) _Pragma("unroll") for (int k = 0; k < 2; ++k) \
;         acc[ai][bj][m][n] = __builtin_amdgcn_mfma_f32_16x16x32_bf16(Bt[n][k], At[m][k], acc[ai][bj][m][n], 0, 0, 0); __builtin_amdgcn_s_setprio(0); } while (0)
; #define PG8_WAIT_V(n) asm volatile("s_waitcnt vmcnt(" #n ")" ::: "memory")
; #define PG8_WAIT_L(n) asm volatile("s_waitcnt lgkmcnt(" #n ")" ::: "memory")
; #define PG8_BAR __builtin_amdgcn_s_barrier()
; #define PG8_SCHED __builtin_amdgcn_sched_barrier(0)
; template <class Epi, class Sched, bool ALIGN_EPI>
; __device__ __forceinline__ void gemm_phase(PG8_LAS unsigned char* lds, const Gemm g, const Sched& S, const Epi& E) {
;     ...
;             PG8_WAIT_V(8); PG8_WAIT_L(0); PG8_BAR; PG8_MMA(0, 0, At, B0); PG8_MMA(0, 1, At, B1); PG8_BAR; PG8_SCHED;
;             PG8_LDA(At, 0, 1); PG8_STAGE(PG8_SB(0, 0), b2, voffB); PG8_STAGE(PG8_SB(0, 1), b2 + hstepB, voffB); PG8_STAGE(PG8_SA(0, 0), a2, voffA);
;             PG8_WAIT_V(8); PG8_WAIT_L(0); PG8_BAR; PG8_MMA(1, 0, At, B0); PG8_MMA(1, 1, At, B1); PG8_BAR; PG8_SCHED;
;             PG8_LDB(B0, 1, 0); PG8_LDB(B1, 1, 1); PG8_SCHED; PG8_LDA(At, 1, 0); PG8_STAGE(PG8_SA(0, 1), a2 + hstepA, voffA);
	s_setprio 1
	v_mfma_f32_16x16x32_bf16 v[126:129], v[158:161], v[194:197], v[126:129]
	v_mfma_f32_16x16x32_bf16 v[126:129], v[162:165], v[198:201], v[126:129]
	v_mfma_f32_16x16x32_bf16 v[122:125], v[174:177], v[198:201], v[122:125]
	v_mfma_f32_16x16x32_bf16 v[122:125], v[166:169], v[194:197], v[122:125]
	v_mfma_f32_16x16x32_bf16 v[114:117], v[178:181], v[194:197], v[114:117]
	v_mfma_f32_16x16x32_bf16 v[114:117], v[182:185], v[198:201], v[114:117]
	v_mfma_f32_16x16x32_bf16 v[106:109], v[190:193], v[198:201], v[106:109]
	v_mfma_f32_16x16x32_bf16 v[106:109], v[186:189], v[194:197], v[106:109]
	v_mfma_f32_16x16x32_bf16 v[90:93], v[186:189], v[202:205], v[90:93]
	v_mfma_f32_16x16x32_bf16 v[90:93], v[190:193], v[206:209], v[90:93]
	v_mfma_f32_16x16x32_bf16 v[98:101], v[182:185], v[206:209], v[98:101]
	v_mfma_f32_16x16x32_bf16 v[98:101], v[178:181], v[202:205], v[98:101]
	v_mfma_f32_16x16x32_bf16 v[110:113], v[166:169], v[202:205], v[110:113]
	v_mfma_f32_16x16x32_bf16 v[110:113], v[174:177], v[206:209], v[110:113]
	v_mfma_f32_16x16x32_bf16 v[118:121], v[162:165], v[206:209], v[118:121]
	v_mfma_f32_16x16x32_bf16 v[118:121], v[158:161], v[202:205], v[118:121]
	v_mfma_f32_16x16x32_bf16 v[102:105], v[158:161], v[210:213], v[102:105]
	v_mfma_f32_16x16x32_bf16 v[102:105], v[162:165], v[214:217], v[102:105]
	v_mfma_f32_16x16x32_bf16 v[94:97], v[174:177], v[214:217], v[94:97]
	v_mfma_f32_16x16x32_bf16 v[94:97], v[166:169], v[210:213], v[94:97]
	v_mfma_f32_16x16x32_bf16 v[82:85], v[178:181], v[210:213], v[82:85]
	v_mfma_f32_16x16x32_bf16 v[82:85], v[182:185], v[214:217], v[82:85]
	v_mfma_f32_16x16x32_bf16 v[74:77], v[190:193], v[214:217], v[74:77]
	v_mfma_f32_16x16x32_bf16 v[74:77], v[186:189], v[210:213], v[74:77]
	v_mfma_f32_16x16x32_bf16 v[66:69], v[186:189], v[218:221], v[66:69]
	v_mfma_f32_16x16x32_bf16 v[66:69], v[190:193], v[222:225], v[66:69]
	v_mfma_f32_16x16x32_bf16 v[70:73], v[182:185], v[222:225], v[70:73]
	v_mfma_f32_16x16x32_bf16 v[70:73], v[178:181], v[218:221], v[70:73]
	v_mfma_f32_16x16x32_bf16 v[78:81], v[166:169], v[218:221], v[78:81]
	v_mfma_f32_16x16x32_bf16 v[78:81], v[174:177], v[222:225], v[78:81]
	v_mfma_f32_16x16x32_bf16 v[86:89], v[162:165], v[222:225], v[86:89]
	v_mfma_f32_16x16x32_bf16 v[86:89], v[158:161], v[218:221], v[86:89]
	v_mfma_f32_16x16x32_bf16 v[62:65], v[158:161], v[226:229], v[62:65]
	v_mfma_f32_16x16x32_bf16 v[62:65], v[162:165], v[230:233], v[62:65]
	v_mfma_f32_16x16x32_bf16 v[58:61], v[174:177], v[230:233], v[58:61]
	v_mfma_f32_16x16x32_bf16 v[58:61], v[166:169], v[226:229], v[58:61]
	v_mfma_f32_16x16x32_bf16 v[50:53], v[178:181], v[226:229], v[50:53]
	v_mfma_f32_16x16x32_bf16 v[50:53], v[182:185], v[230:233], v[50:53]
	v_mfma_f32_16x16x32_bf16 v[42:45], v[190:193], v[230:233], v[42:45]
	v_mfma_f32_16x16x32_bf16 v[42:45], v[186:189], v[226:229], v[42:45]
	v_mfma_f32_16x16x32_bf16 v[26:29], v[186:189], v[234:237], v[26:29]
	v_mfma_f32_16x16x32_bf16 v[26:29], v[190:193], v[238:241], v[26:29]
	v_mfma_f32_16x16x32_bf16 v[34:37], v[182:185], v[238:241], v[34:37]
	v_mfma_f32_16x16x32_bf16 v[34:37], v[178:181], v[234:237], v[34:37]
	v_mfma_f32_16x16x32_bf16 v[46:49], v[166:169], v[234:237], v[46:49]
	v_mfma_f32_16x16x32_bf16 v[46:49], v[174:177], v[238:241], v[46:49]
	v_mfma_f32_16x16x32_bf16 v[54:57], v[162:165], v[238:241], v[54:57]
	v_mfma_f32_16x16x32_bf16 v[54:57], v[158:161], v[234:237], v[54:57]
	v_mfma_f32_16x16x32_bf16 v[38:41], v[158:161], v[242:245], v[38:41]
	v_mfma_f32_16x16x32_bf16 v[38:41], v[162:165], v[246:249], v[38:41]
	v_mfma_f32_16x16x32_bf16 v[30:33], v[174:177], v[246:249], v[30:33]
	v_mfma_f32_16x16x32_bf16 v[30:33], v[166:169], v[242:245], v[30:33]
	v_mfma_f32_16x16x32_bf16 v[18:21], v[178:181], v[242:245], v[18:21]
	v_mfma_f32_16x16x32_bf16 v[18:21], v[182:185], v[246:249], v[18:21]
	v_mfma_f32_16x16x32_bf16 v[10:13], v[190:193], v[246:249], v[10:13]
	v_mfma_f32_16x16x32_bf16 v[10:13], v[186:189], v[242:245], v[10:13]
	v_mfma_f32_16x16x32_bf16 v[2:5], v[186:189], v[250:253], v[2:5]
	v_mfma_f32_16x16x32_bf16 v[2:5], v[190:193], v[142:145], v[2:5]
	v_mfma_f32_16x16x32_bf16 v[6:9], v[182:185], v[142:145], v[6:9]
	v_mfma_f32_16x16x32_bf16 v[6:9], v[178:181], v[250:253], v[6:9]
	v_mfma_f32_16x16x32_bf16 v[14:17], v[166:169], v[250:253], v[14:17]
	v_mfma_f32_16x16x32_bf16 v[14:17], v[174:177], v[142:145], v[14:17]
	v_mfma_f32_16x16x32_bf16 v[22:25], v[162:165], v[142:145], v[22:25]
	v_mfma_f32_16x16x32_bf16 v[22:25], v[158:161], v[250:253], v[22:25]
	s_setprio 0
	s_waitcnt vmcnt(0)
	s_barrier
	s_cmp_eq_u32 s57, 43
	s_cselect_b32 s28, s58, s28
	s_cselect_b32 s29, s59, s29
	s_add_i32 m0, s60, 0x10000
	s_nop 0
	global_load_lds_dwordx4 v132, s[28:29]
	s_add_i32 m0, s60, 0x12000
	s_nop 0
	global_load_lds_dwordx4 v136, s[28:29]
	s_add_u32 s30, s28, 0x58000
	s_addc_u32 s31, s29, 0
	s_add_i32 m0, s60, 0x11000
	s_nop 0
	global_load_lds_dwordx4 v132, s[30:31]
	s_add_i32 m0, s60, 0x13000
	s_nop 0
	global_load_lds_dwordx4 v136, s[30:31]
	s_add_u32 s30, s28, 0x160000
	s_addc_u32 s31, s29, 0
	s_add_i32 m0, s60, 0x14000
	s_nop 0
	global_load_lds_dwordx4 v132, s[30:31]
	s_add_i32 m0, s60, 0x16000
	s_nop 0
	global_load_lds_dwordx4 v136, s[30:31]
	s_add_u32 s30, s28, 0x1b8000
	s_addc_u32 s31, s29, 0
	s_add_i32 m0, s60, 0x15000
	s_nop 0
	global_load_lds_dwordx4 v132, s[30:31]
	s_add_i32 m0, s60, 0x17000
	s_nop 0
	global_load_lds_dwordx4 v136, s[30:31]
	s_add_u32 s28, s28, 0x80
	s_addc_u32 s29, s29, 0
	ds_read_b128 v[194:197], v157 offset:32768
	ds_read_b128 v[198:201], v157 offset:33792
	ds_read_b128 v[202:205], v157 offset:34816
	ds_read_b128 v[206:209], v157 offset:35840
	ds_read_b128 v[210:213], v157 offset:36864
	ds_read_b128 v[214:217], v157 offset:37888
	ds_read_b128 v[218:221], v157 offset:38912
	ds_read_b128 v[222:225], v157 offset:39936
	ds_read_b128 v[158:161], v155 offset:32768
	ds_read_b128 v[162:165], v155 offset:33792
	ds_read_b128 v[166:169], v155 offset:34816
	ds_read_b128 v[174:177], v155 offset:35840
	ds_read_b128 v[178:181], v155 offset:49152
	ds_read_b128 v[182:185], v155 offset:50176
	ds_read_b128 v[186:189], v155 offset:51200
	ds_read_b128 v[190:193], v155 offset:52224
	ds_read_b128 v[226:229], v157 offset:49152
	ds_read_b128 v[230:233], v157 offset:50176
	ds_read_b128 v[234:237], v157 offset:51200
	ds_read_b128 v[238:241], v157 offset:52224
	ds_read_b128 v[242:245], v157 offset:53248
	ds_read_b128 v[246:249], v157 offset:54272
	ds_read_b128 v[250:253], v157 offset:55296
	ds_read_b128 v[142:145], v157 offset:56320
	s_waitcnt vmcnt(8) lgkmcnt(0)
	s_barrier
; #define PG8_STAGE(bufoff, gbase, voff) do { _Pragma("unroll") for (int _i = 0; _i < 2; ++_i) \
;         __builtin_amdgcn_global_load_lds((const unsigned*)((const char*)(gbase) + (voff)[_i]), (PG8_LAS unsigned*)(lds + (bufoff) + ldsw + _i * 8192), 16, 0, 0); } while (0)
; #define PG8_LDA(dst, b, h) do { _Pragma("unroll") for (int m = 0; m < 4; ++m) _Pragma("unroll") for (int k = 0; k < 2; ++k) dst[m][k] = *(const PG8_LAS bf16x8*)(lds + PG8_SA(b, h) + aoff + m * 2048 + k * 1024); } while (0)
; #define PG8_LDB(dst, b, h) do { _Pragma("unroll") for (int n = 0; n < 2; ++n) _Pragma("unroll") for (int k = 0; k < 2; ++k) dst[n][k] = *(const PG8_LAS bf16x8*)(lds + PG8_SB(b, h) + boff + n * 2048 + k * 1024); } while (0)
; #define PG8_MMA(ai, bj, At, Bt) do { __builtin_amdgcn_s_setprio(1); _Pragma("unroll") for (int m = 0; m < 4; ++m) _Pragma("unroll") for (int n = 0; n < 2; ++n) _Pragma("unroll") for (int k = 0; k < 2; ++k) \
;         acc[ai][bj][m][n] = __builtin_amdgcn_mfma_f32_16x16x32_bf16(Bt[n][k], At[m][k], acc[ai][bj][m][n], 0, 0, 0); __builtin_amdgcn_s_setprio(0); } while (0)
; #define PG8_WAIT_V(n) asm volatile("s_waitcnt vmcnt(" #n ")" ::: "memory")
; #define PG8_WAIT_L(n) asm volatile("s_waitcnt lgkmcnt(" #n ")" ::: "memory")
; #define PG8_BAR __builtin_amdgcn_s_barrier()
; #define PG8_SCHED __builtin_amdgcn_sched_barrier(0)
; template <class Epi, class Sched, bool ALIGN_EPI>
; __device__ __forceinline__ void gemm_phase(PG8_LAS unsigned char* lds, const Gemm g, const Sched& S, const Epi& E) {
;     ...
;             PG8_WAIT_V(8); PG8_WAIT_L(0); PG8_BAR; PG8_MMA(1, 0, At, B0); PG8_MMA(1, 1, At, B1); PG8_BAR; PG8_SCHED;
;             PG8_LDB(B0, 1, 0); PG8_LDB(B1, 1, 1); PG8_SCHED; PG8_LDA(At, 1, 0); PG8_STAGE(PG8_SA(0, 1), a2 + hstepA, voffA);
;             PG8_WAIT_V(8); PG8_WAIT_L(0); PG8_BAR; PG8_MMA(0, 0, At, B0); PG8_MMA(0, 1, At, B1); PG8_BAR; PG8_SCHED;
;             PG8_LDA(At, 1, 1); PG8_STAGE(PG8_SB(1, 0), b3, voffB); PG8_STAGE(PG8_SB(1, 1), b3 + hstepB, voffB); PG8_STAGE(PG8_SA(1, 0), a3, voffA);
;             PG8_WAIT_V(8); PG8_WAIT_L(0); PG8_BAR; PG8_MMA(1, 0, At, B0); PG8_MMA(1, 1, At, B1); PG8_BAR; PG8_SCHED;
	s_setprio 1
	v_mfma_f32_16x16x32_bf16 v[126:129], v[158:161], v[194:197], v[126:129]
	v_mfma_f32_16x16x32_bf16 v[126:129], v[162:165], v[198:201], v[126:129]
	v_mfma_f32_16x16x32_bf16 v[122:125], v[174:177], v[198:201], v[122:125]
	v_mfma_f32_16x16x32_bf16 v[122:125], v[166:169], v[194:197], v[122:125]
	v_mfma_f32_16x16x32_bf16 v[114:117], v[178:181], v[194:197], v[114:117]
	v_mfma_f32_16x16x32_bf16 v[114:117], v[182:185], v[198:201], v[114:117]
	v_mfma_f32_16x16x32_bf16 v[106:109], v[190:193], v[198:201], v[106:109]
	v_mfma_f32_16x16x32_bf16 v[106:109], v[186:189], v[194:197], v[106:109]
	v_mfma_f32_16x16x32_bf16 v[90:93], v[186:189], v[202:205], v[90:93]
	v_mfma_f32_16x16x32_bf16 v[90:93], v[190:193], v[206:209], v[90:93]
	v_mfma_f32_16x16x32_bf16 v[98:101], v[182:185], v[206:209], v[98:101]
	v_mfma_f32_16x16x32_bf16 v[98:101], v[178:181], v[202:205], v[98:101]
	v_mfma_f32_16x16x32_bf16 v[110:113], v[166:169], v[202:205], v[110:113]
	v_mfma_f32_16x16x32_bf16 v[110:113], v[174:177], v[206:209], v[110:113]
	v_mfma_f32_16x16x32_bf16 v[118:121], v[162:165], v[206:209], v[118:121]
	v_mfma_f32_16x16x32_bf16 v[118:121], v[158:161], v[202:205], v[118:121]
	v_mfma_f32_16x16x32_bf16 v[102:105], v[158:161], v[210:213], v[102:105]
	v_mfma_f32_16x16x32_bf16 v[102:105], v[162:165], v[214:217], v[102:105]
	v_mfma_f32_16x16x32_bf16 v[94:97], v[174:177], v[214:217], v[94:97]
	v_mfma_f32_16x16x32_bf16 v[94:97], v[166:169], v[210:213], v[94:97]
	v_mfma_f32_16x16x32_bf16 v[82:85], v[178:181], v[210:213], v[82:85]
	v_mfma_f32_16x16x32_bf16 v[82:85], v[182:185], v[214:217], v[82:85]
	v_mfma_f32_16x16x32_bf16 v[74:77], v[190:193], v[214:217], v[74:77]
	v_mfma_f32_16x16x32_bf16 v[74:77], v[186:189], v[210:213], v[74:77]
	v_mfma_f32_16x16x32_bf16 v[66:69], v[186:189], v[218:221], v[66:69]
	v_mfma_f32_16x16x32_bf16 v[66:69], v[190:193], v[222:225], v[66:69]
	v_mfma_f32_16x16x32_bf16 v[70:73], v[182:185], v[222:225], v[70:73]
	v_mfma_f32_16x16x32_bf16 v[70:73], v[178:181], v[218:221], v[70:73]
	v_mfma_f32_16x16x32_bf16 v[78:81], v[166:169], v[218:221], v[78:81]
	v_mfma_f32_16x16x32_bf16 v[78:81], v[174:177], v[222:225], v[78:81]
	v_mfma_f32_16x16x32_bf16 v[86:89], v[162:165], v[222:225], v[86:89]
	v_mfma_f32_16x16x32_bf16 v[86:89], v[158:161], v[218:221], v[86:89]
	v_mfma_f32_16x16x32_bf16 v[62:65], v[158:161], v[226:229], v[62:65]
	v_mfma_f32_16x16x32_bf16 v[62:65], v[162:165], v[230:233], v[62:65]
	v_mfma_f32_16x16x32_bf16 v[58:61], v[174:177], v[230:233], v[58:61]
	v_mfma_f32_16x16x32_bf16 v[58:61], v[166:169], v[226:229], v[58:61]
	v_mfma_f32_16x16x32_bf16 v[50:53], v[178:181], v[226:229], v[50:53]
	v_mfma_f32_16x16x32_bf16 v[50:53], v[182:185], v[230:233], v[50:53]
	v_mfma_f32_16x16x32_bf16 v[42:45], v[190:193], v[230:233], v[42:45]
	v_mfma_f32_16x16x32_bf16 v[42:45], v[186:189], v[226:229], v[42:45]
	v_mfma_f32_16x16x32_bf16 v[26:29], v[186:189], v[234:237], v[26:29]
	v_mfma_f32_16x16x32_bf16 v[26:29], v[190:193], v[238:241], v[26:29]
	v_mfma_f32_16x16x32_bf16 v[34:37], v[182:185], v[238:241], v[34:37]
	v_mfma_f32_16x16x32_bf16 v[34:37], v[178:181], v[234:237], v[34:37]
	v_mfma_f32_16x16x32_bf16 v[46:49], v[166:169], v[234:237], v[46:49]
	v_mfma_f32_16x16x32_bf16 v[46:49], v[174:177], v[238:241], v[46:49]
	v_mfma_f32_16x16x32_bf16 v[54:57], v[162:165], v[238:241], v[54:57]
	v_mfma_f32_16x16x32_bf16 v[54:57], v[158:161], v[234:237], v[54:57]
	v_mfma_f32_16x16x32_bf16 v[38:41], v[158:161], v[242:245], v[38:41]
	v_mfma_f32_16x16x32_bf16 v[38:41], v[162:165], v[246:249], v[38:41]
	v_mfma_f32_16x16x32_bf16 v[30:33], v[174:177], v[246:249], v[30:33]
	v_mfma_f32_16x16x32_bf16 v[30:33], v[166:169], v[242:245], v[30:33]
	v_mfma_f32_16x16x32_bf16 v[18:21], v[178:181], v[242:245], v[18:21]
	v_mfma_f32_16x16x32_bf16 v[18:21], v[182:185], v[246:249], v[18:21]
	v_mfma_f32_16x16x32_bf16 v[10:13], v[190:193], v[246:249], v[10:13]
	v_mfma_f32_16x16x32_bf16 v[10:13], v[186:189], v[242:245], v[10:13]
	v_mfma_f32_16x16x32_bf16 v[2:5], v[186:189], v[250:253], v[2:5]
	v_mfma_f32_16x16x32_bf16 v[2:5], v[190:193], v[142:145], v[2:5]
	v_mfma_f32_16x16x32_bf16 v[6:9], v[182:185], v[142:145], v[6:9]
	v_mfma_f32_16x16x32_bf16 v[6:9], v[178:181], v[250:253], v[6:9]
	v_mfma_f32_16x16x32_bf16 v[14:17], v[166:169], v[250:253], v[14:17]
	v_mfma_f32_16x16x32_bf16 v[14:17], v[174:177], v[142:145], v[14:17]
	v_mfma_f32_16x16x32_bf16 v[22:25], v[162:165], v[142:145], v[22:25]
	v_mfma_f32_16x16x32_bf16 v[22:25], v[158:161], v[250:253], v[22:25]
	s_setprio 0
	s_waitcnt vmcnt(0)
	s_barrier
	s_add_i32 s57, s57, 1
	s_cmp_lt_u32 s57, 44
	s_cbranch_scc1 .Lp9k_A_loop
	s_branch .Lp9k_done
.Lp9k_B_init:
	s_sub_u32 s28, s26, 0x57f80
	s_subb_u32 s29, s27, 0
	s_sub_u32 s58, s6, 0x58000
	s_subb_u32 s59, s7, 0
; #define PG8_STAGE(bufoff, gbase, voff) do { _Pragma("unroll") for (int _i = 0; _i < 2; ++_i) \
;         __builtin_amdgcn_global_load_lds((const unsigned*)((const char*)(gbase) + (voff)[_i]), (PG8_LAS unsigned*)(lds + (bufoff) + ldsw + _i * 8192), 16, 0, 0); } while (0)
; #define PG8_LDA(dst, b, h) do { _Pragma("unroll") for (int m = 0; m < 4; ++m) _Pragma("unroll") for (int k = 0; k < 2; ++k) dst[m][k] = *(const PG8_LAS bf16x8*)(lds + PG8_SA(b, h) + aoff + m * 2048 + k * 1024); } while (0)
; #define PG8_LDB(dst, b, h) do { _Pragma("unroll") for (int n = 0; n < 2; ++n) _Pragma("unroll") for (int k = 0; k < 2; ++k) dst[n][k] = *(const PG8_LAS bf16x8*)(lds + PG8_SB(b, h) + boff + n * 2048 + k * 1024); } while (0)
; #define PG8_MMA(ai, bj, At, Bt) do { __builtin_amdgcn_s_setprio(1); _Pragma("unroll") for (int m = 0; m < 4; ++m) _Pragma("unroll") for (int n = 0; n < 2; ++n) _Pragma("unroll") for (int k = 0; k < 2; ++k) \
;         acc[ai][bj][m][n] = __builtin_amdgcn_mfma_f32_16x16x32_bf16(Bt[n][k], At[m][k], acc[ai][bj][m][n], 0, 0, 0); __builtin_amdgcn_s_setprio(0); } while (0)
; #define PG8_WAIT_V(n) asm volatile("s_waitcnt vmcnt(" #n ")" ::: "memory")
; #define PG8_WAIT_L(n) asm volatile("s_waitcnt lgkmcnt(" #n ")" ::: "memory")
; #define PG8_BAR __builtin_amdgcn_s_barrier()
; #define PG8_SCHED __builtin_amdgcn_sched_barrier(0)
; template <class Epi, class Sched, bool ALIGN_EPI>
; __device__ __forceinline__ void gemm_phase(PG8_LAS unsigned char* lds, const Gemm g, const Sched& S, const Epi& E) {
;     ...
;             PG8_LDB(B0, 0, 0); PG8_LDB(B1, 0, 1); PG8_SCHED; PG8_LDA(At, 0, 0); PG8_STAGE(PG8_SA(1, 1), a1 + hstepA, voffA);
;             PG8_WAIT_V(8); PG8_WAIT_L(0); PG8_BAR; PG8_MMA(0, 0, At, B0); PG8_MMA(0, 1, At, B1); PG8_BAR; PG8_SCHED;
;             PG8_LDA(At, 0, 1); PG8_STAGE(PG8_SB(0, 0), b2, voffB); PG8_STAGE(PG8_SB(0, 1), b2 + hstepB, voffB); PG8_STAGE(PG8_SA(0, 0), a2, voffA);
;             PG8_WAIT_V(8); PG8_WAIT_L(0); PG8_BAR; PG8_MMA(1, 0, At, B0); PG8_MMA(1, 1, At, B1); PG8_BAR; PG8_SCHED;
.Lp9k_B_loop:
	s_add_i32 m0, s60, 0xa000
	s_nop 0
	global_load_lds_dwordx4 v134, s[28:29]
	s_add_u32 s30, s28, 0x58000
	s_addc_u32 s31, s29, 0
	s_add_i32 m0, s60, 0xb000
	s_nop 0
	global_load_lds_dwordx4 v134, s[30:31]
	s_add_u32 s30, s28, 0x160000
	s_addc_u32 s31, s29, 0
	s_add_i32 m0, s60, 0xe000
	s_nop 0
	global_load_lds_dwordx4 v134, s[30:31]
	s_add_u32 s30, s28, 0x1b8000
	s_addc_u32 s31, s29, 0
	s_add_i32 m0, s60, 0xf000
	s_nop 0
	global_load_lds_dwordx4 v134, s[30:31]
	s_add_u32 s34, s28, 0x80
	s_addc_u32 s35, s29, 0
	s_cmp_eq_u32 s57, 43
	s_cselect_b32 s34, s58, s34
	s_cselect_b32 s35, s59, s35
	s_add_i32 m0, s60, 0x0
	s_nop 0
	global_load_lds_dwordx4 v130, s[34:35]
	s_add_u32 s30, s34, 0x58000
	s_addc_u32 s31, s35, 0
	s_add_i32 m0, s60, 0x1000
	s_nop 0
	global_load_lds_dwordx4 v130, s[30:31]
	s_add_u32 s30, s34, 0x160000
	s_addc_u32 s31, s35, 0
	s_add_i32 m0, s60, 0x4000
	s_nop 0
	global_load_lds_dwordx4 v130, s[30:31]
	s_add_u32 s30, s34, 0x1b8000
	s_addc_u32 s31, s35, 0
	s_add_i32 m0, s60, 0x5000
	s_nop 0
	global_load_lds_dwordx4 v130, s[30:31]
	s_add_u32 s28, s28, 0x80
	s_addc_u32 s29, s29, 0
	ds_read_b128 v[194:197], v157 offset:0
	ds_read_b128 v[198:201], v157 offset:1024
	ds_read_b128 v[202:205], v157 offset:2048
	ds_read_b128 v[206:209], v157 offset:3072
	ds_read_b128 v[210:213], v157 offset:4096
	ds_read_b128 v[214:217], v157 offset:5120
	ds_read_b128 v[218:221], v157 offset:6144
	ds_read_b128 v[222:225], v157 offset:7168
	ds_read_b128 v[158:161], v155 offset:0
	ds_read_b128 v[162:165], v155 offset:1024
	ds_read_b128 v[166:169], v155 offset:2048
	ds_read_b128 v[174:177], v155 offset:3072
	ds_read_b128 v[178:181], v155 offset:16384
	ds_read_b128 v[182:185], v155 offset:17408
	ds_read_b128 v[186:189], v155 offset:18432
	ds_read_b128 v[190:193], v155 offset:19456
	ds_read_b128 v[226:229], v157 offset:16384
	ds_read_b128 v[230:233], v157 offset:17408
	ds_read_b128 v[234:237], v157 offset:18432
	ds_read_b128 v[238:241], v157 offset:19456
	ds_read_b128 v[242:245], v157 offset:20480
	ds_read_b128 v[246:249], v157 offset:21504
	ds_read_b128 v[250:253], v157 offset:22528
	ds_read_b128 v[142:145], v157 offset:23552
	s_waitcnt vmcnt(8) lgkmcnt(0)
	s_barrier
	s_setprio 1
	v_mfma_f32_16x16x32_bf16 v[126:129], v[158:161], v[194:197], v[126:129]
	v_mfma_f32_16x16x32_bf16 v[126:129], v[162:165], v[198:201], v[126:129]
	v_mfma_f32_16x16x32_bf16 v[122:125], v[174:177], v[198:201], v[122:125]
	v_mfma_f32_16x16x32_bf16 v[122:125], v[166:169], v[194:197], v[122:125]
	v_mfma_f32_16x16x32_bf16 v[114:117], v[178:181], v[194:197], v[114:117]
	v_mfma_f32_16x16x32_bf16 v[114:117], v[182:185], v[198:201], v[114:117]
	v_mfma_f32_16x16x32_bf16 v[106:109], v[190:193], v[198:201], v[106:109]
	v_mfma_f32_16x16x32_bf16 v[106:109], v[186:189], v[194:197], v[106:109]
	v_mfma_f32_16x16x32_bf16 v[90:93], v[186:189], v[202:205], v[90:93]
	v_mfma_f32_16x16x32_bf16 v[90:93], v[190:193], v[206:209], v[90:93]
	v_mfma_f32_16x16x32_bf16 v[98:101], v[182:185], v[206:209], v[98:101]
	v_mfma_f32_16x16x32_bf16 v[98:101], v[178:181], v[202:205], v[98:101]
	v_mfma_f32_16x16x32_bf16 v[110:113], v[166:169], v[202:205], v[110:113]
	v_mfma_f32_16x16x32_bf16 v[110:113], v[174:177], v[206:209], v[110:113]
	v_mfma_f32_16x16x32_bf16 v[118:121], v[162:165], v[206:209], v[118:121]
	v_mfma_f32_16x16x32_bf16 v[118:121], v[158:161], v[202:205], v[118:121]
	v_mfma_f32_16x16x32_bf16 v[102:105], v[158:161], v[210:213], v[102:105]
	v_mfma_f32_16x16x32_bf16 v[102:105], v[162:165], v[214:217], v[102:105]
	v_mfma_f32_16x16x32_bf16 v[94:97], v[174:177], v[214:217], v[94:97]
	v_mfma_f32_16x16x32_bf16 v[94:97], v[166:169], v[210:213], v[94:97]
	v_mfma_f32_16x16x32_bf16 v[82:85], v[178:181], v[210:213], v[82:85]
	v_mfma_f32_16x16x32_bf16 v[82:85], v[182:185], v[214:217], v[82:85]
	v_mfma_f32_16x16x32_bf16 v[74:77], v[190:193], v[214:217], v[74:77]
	v_mfma_f32_16x16x32_bf16 v[74:77], v[186:189], v[210:213], v[74:77]
	v_mfma_f32_16x16x32_bf16 v[66:69], v[186:189], v[218:221], v[66:69]
	v_mfma_f32_16x16x32_bf16 v[66:69], v[190:193], v[222:225], v[66:69]
	v_mfma_f32_16x16x32_bf16 v[70:73], v[182:185], v[222:225], v[70:73]
	v_mfma_f32_16x16x32_bf16 v[70:73], v[178:181], v[218:221], v[70:73]
	v_mfma_f32_16x16x32_bf16 v[78:81], v[166:169], v[218:221], v[78:81]
	v_mfma_f32_16x16x32_bf16 v[78:81], v[174:177], v[222:225], v[78:81]
	v_mfma_f32_16x16x32_bf16 v[86:89], v[162:165], v[222:225], v[86:89]
	v_mfma_f32_16x16x32_bf16 v[86:89], v[158:161], v[218:221], v[86:89]
	v_mfma_f32_16x16x32_bf16 v[62:65], v[158:161], v[226:229], v[62:65]
	v_mfma_f32_16x16x32_bf16 v[62:65], v[162:165], v[230:233], v[62:65]
	v_mfma_f32_16x16x32_bf16 v[58:61], v[174:177], v[230:233], v[58:61]
	v_mfma_f32_16x16x32_bf16 v[58:61], v[166:169], v[226:229], v[58:61]
	v_mfma_f32_16x16x32_bf16 v[50:53], v[178:181], v[226:229], v[50:53]
	v_mfma_f32_16x16x32_bf16 v[50:53], v[182:185], v[230:233], v[50:53]
	v_mfma_f32_16x16x32_bf16 v[42:45], v[190:193], v[230:233], v[42:45]
	v_mfma_f32_16x16x32_bf16 v[42:45], v[186:189], v[226:229], v[42:45]
	v_mfma_f32_16x16x32_bf16 v[26:29], v[186:189], v[234:237], v[26:29]
	v_mfma_f32_16x16x32_bf16 v[26:29], v[190:193], v[238:241], v[26:29]
	v_mfma_f32_16x16x32_bf16 v[34:37], v[182:185], v[238:241], v[34:37]
	v_mfma_f32_16x16x32_bf16 v[34:37], v[178:181], v[234:237], v[34:37]
	v_mfma_f32_16x16x32_bf16 v[46:49], v[166:169], v[234:237], v[46:49]
	v_mfma_f32_16x16x32_bf16 v[46:49], v[174:177], v[238:241], v[46:49]
	v_mfma_f32_16x16x32_bf16 v[54:57], v[162:165], v[238:241], v[54:57]
	v_mfma_f32_16x16x32_bf16 v[54:57], v[158:161], v[234:237], v[54:57]
	v_mfma_f32_16x16x32_bf16 v[38:41], v[158:161], v[242:245], v[38:41]
	v_mfma_f32_16x16x32_bf16 v[38:41], v[162:165], v[246:249], v[38:41]
	v_mfma_f32_16x16x32_bf16 v[30:33], v[174:177], v[246:249], v[30:33]
	v_mfma_f32_16x16x32_bf16 v[30:33], v[166:169], v[242:245], v[30:33]
	v_mfma_f32_16x16x32_bf16 v[18:21], v[178:181], v[242:245], v[18:21]
	v_mfma_f32_16x16x32_bf16 v[18:21], v[182:185], v[246:249], v[18:21]
	v_mfma_f32_16x16x32_bf16 v[10:13], v[190:193], v[246:249], v[10:13]
	v_mfma_f32_16x16x32_bf16 v[10:13], v[186:189], v[242:245], v[10:13]
	v_mfma_f32_16x16x32_bf16 v[2:5], v[186:189], v[250:253], v[2:5]
	v_mfma_f32_16x16x32_bf16 v[2:5], v[190:193], v[142:145], v[2:5]
	v_mfma_f32_16x16x32_bf16 v[6:9], v[182:185], v[142:145], v[6:9]
	v_mfma_f32_16x16x32_bf16 v[6:9], v[178:181], v[250:253], v[6:9]
	v_mfma_f32_16x16x32_bf16 v[14:17], v[166:169], v[250:253], v[14:17]
	v_mfma_f32_16x16x32_bf16 v[14:17], v[174:177], v[142:145], v[14:17]
	v_mfma_f32_16x16x32_bf16 v[22:25], v[162:165], v[142:145], v[22:25]
	v_mfma_f32_16x16x32_bf16 v[22:25], v[158:161], v[250:253], v[22:25]
	s_setprio 0
	s_waitcnt vmcnt(0)
	s_barrier
; #define PG8_STAGE(bufoff, gbase, voff) do { _Pragma("unroll") for (int _i = 0; _i < 2; ++_i) \
;         __builtin_amdgcn_global_load_lds((const unsigned*)((const char*)(gbase) + (voff)[_i]), (PG8_LAS unsigned*)(lds + (bufoff) + ldsw + _i * 8192), 16, 0, 0); } while (0)
; #define PG8_LDA(dst, b, h) do { _Pragma("unroll") for (int m = 0; m < 4; ++m) _Pragma("unroll") for (int k = 0; k < 2; ++k) dst[m][k] = *(const PG8_LAS bf16x8*)(lds + PG8_SA(b, h) + aoff + m * 2048 + k * 1024); } while (0)
; #define PG8_LDB(dst, b, h) do { _Pragma("unroll") for (int n = 0; n < 2; ++n) _Pragma("unroll") for (int k = 0; k < 2; ++k) dst[n][k] = *(const PG8_LAS bf16x8*)(lds + PG8_SB(b, h) + boff + n * 2048 + k * 1024); } while (0)
; #define PG8_MMA(ai, bj, At, Bt) do { __builtin_amdgcn_s_setprio(1); _Pragma("unroll") for (int m = 0; m < 4; ++m) _Pragma("unroll") for (int n = 0; n < 2; ++n) _Pragma("unroll") for (int k = 0; k < 2; ++k) \
;         acc[ai][bj][m][n] = __builtin_amdgcn_mfma_f32_16x16x32_bf16(Bt[n][k], At[m][k], acc[ai][bj][m][n], 0, 0, 0); __builtin_amdgcn_s_setprio(0); } while (0)
; #define PG8_WAIT_V(n) asm volatile("s_waitcnt vmcnt(" #n ")" ::: "memory")
; #define PG8_WAIT_L(n) asm volatile("s_waitcnt lgkmcnt(" #n ")" ::: "memory")
; #define PG8_BAR __builtin_amdgcn_s_barrier()
; #define PG8_SCHED __builtin_amdgcn_sched_barrier(0)
; template <class Epi, class Sched, bool ALIGN_EPI>
; __device__ __forceinline__ void gemm_phase(PG8_LAS unsigned char* lds, const Gemm g, const Sched& S, const Epi& E) {
;     ...
;             PG8_LDB(B0, 1, 0); PG8_LDB(B1, 1, 1); PG8_SCHED; PG8_LDA(At, 1, 0); PG8_STAGE(PG8_SA(0, 1), a2 + hstepA, voffA);
;             PG8_WAIT_V(8); PG8_WAIT_L(0); PG8_BAR; PG8_MMA(0, 0, At, B0); PG8_MMA(0, 1, At, B1); PG8_BAR; PG8_SCHED;
;             PG8_LDA(At, 1, 1); PG8_STAGE(PG8_SB(1, 0), b3, voffB); PG8_STAGE(PG8_SB(1, 1), b3 + hstepB, voffB); PG8_STAGE(PG8_SA(1, 0), a3, voffA);
;             PG8_WAIT_V(8); PG8_WAIT_L(0); PG8_BAR; PG8_MMA(1, 0, At, B0); PG8_MMA(1, 1, At, B1); PG8_BAR; PG8_SCHED;
;         }
	s_cmp_eq_u32 s57, 43
	s_cselect_b32 s28, s58, s28
	s_cselect_b32 s29, s59, s29
	s_add_i32 m0, s60, 0x2000
	s_nop 0
	global_load_lds_dwordx4 v134, s[28:29]
	s_add_u32 s30, s28, 0x58000
	s_addc_u32 s31, s29, 0
	s_add_i32 m0, s60, 0x3000
	s_nop 0
	global_load_lds_dwordx4 v134, s[30:31]
	s_add_u32 s30, s28, 0x160000
	s_addc_u32 s31, s29, 0
	s_add_i32 m0, s60, 0x6000
	s_nop 0
	global_load_lds_dwordx4 v134, s[30:31]
	s_add_u32 s30, s28, 0x1b8000
	s_addc_u32 s31, s29, 0
	s_add_i32 m0, s60, 0x7000
	s_nop 0
	global_load_lds_dwordx4 v134, s[30:31]
	s_add_u32 s34, s28, 0x80
	s_addc_u32 s35, s29, 0
	s_add_i32 m0, s60, 0x8000
	s_nop 0
	global_load_lds_dwordx4 v130, s[34:35]
	s_add_u32 s30, s34, 0x58000
	s_addc_u32 s31, s35, 0
	s_add_i32 m0, s60, 0x9000
	s_nop 0
	global_load_lds_dwordx4 v130, s[30:31]
	s_add_u32 s30, s34, 0x160000
	s_addc_u32 s31, s35, 0
	s_add_i32 m0, s60, 0xc000
	s_nop 0
	global_load_lds_dwordx4 v130, s[30:31]
	s_add_u32 s30, s34, 0x1b8000
	s_addc_u32 s31, s35, 0
	s_add_i32 m0, s60, 0xd000
	s_nop 0
	global_load_lds_dwordx4 v130, s[30:31]
	s_add_u32 s28, s28, 0x80
	s_addc_u32 s29, s29, 0
	ds_read_b128 v[194:197], v157 offset:32768
	ds_read_b128 v[198:201], v157 offset:33792
	ds_read_b128 v[202:205], v157 offset:34816
	ds_read_b128 v[206:209], v157 offset:35840
	ds_read_b128 v[210:213], v157 offset:36864
	ds_read_b128 v[214:217], v157 offset:37888
	ds_read_b128 v[218:221], v157 offset:38912
	ds_read_b128 v[222:225], v157 offset:39936
	ds_read_b128 v[158:161], v155 offset:32768
	ds_read_b128 v[162:165], v155 offset:33792
	ds_read_b128 v[166:169], v155 offset:34816
	ds_read_b128 v[174:177], v155 offset:35840
	ds_read_b128 v[178:181], v155 offset:49152
	ds_read_b128 v[182:185], v155 offset:50176
	ds_read_b128 v[186:189], v155 offset:51200
	ds_read_b128 v[190:193], v155 offset:52224
	ds_read_b128 v[226:229], v157 offset:49152
	ds_read_b128 v[230:233], v157 offset:50176
	ds_read_b128 v[234:237], v157 offset:51200
	ds_read_b128 v[238:241], v157 offset:52224
	ds_read_b128 v[242:245], v157 offset:53248
	ds_read_b128 v[246:249], v157 offset:54272
	ds_read_b128 v[250:253], v157 offset:55296
	ds_read_b128 v[142:145], v157 offset:56320
	s_waitcnt vmcnt(8) lgkmcnt(0)
	s_barrier
	s_setprio 1
	v_mfma_f32_16x16x32_bf16 v[126:129], v[158:161], v[194:197], v[126:129]
	v_mfma_f32_16x16x32_bf16 v[126:129], v[162:165], v[198:201], v[126:129]
	v_mfma_f32_16x16x32_bf16 v[122:125], v[174:177], v[198:201], v[122:125]
	v_mfma_f32_16x16x32_bf16 v[122:125], v[166:169], v[194:197], v[122:125]
	v_mfma_f32_16x16x32_bf16 v[114:117], v[178:181], v[194:197], v[114:117]
	v_mfma_f32_16x16x32_bf16 v[114:117], v[182:185], v[198:201], v[114:117]
	v_mfma_f32_16x16x32_bf16 v[106:109], v[190:193], v[198:201], v[106:109]
	v_mfma_f32_16x16x32_bf16 v[106:109], v[186:189], v[194:197], v[106:109]
	v_mfma_f32_16x16x32_bf16 v[90:93], v[186:189], v[202:205], v[90:93]
	v_mfma_f32_16x16x32_bf16 v[90:93], v[190:193], v[206:209], v[90:93]
	v_mfma_f32_16x16x32_bf16 v[98:101], v[182:185], v[206:209], v[98:101]
	v_mfma_f32_16x16x32_bf16 v[98:101], v[178:181], v[202:205], v[98:101]
	v_mfma_f32_16x16x32_bf16 v[110:113], v[166:169], v[202:205], v[110:113]
	v_mfma_f32_16x16x32_bf16 v[110:113], v[174:177], v[206:209], v[110:113]
	v_mfma_f32_16x16x32_bf16 v[118:121], v[162:165], v[206:209], v[118:121]
	v_mfma_f32_16x16x32_bf16 v[118:121], v[158:161], v[202:205], v[118:121]
	v_mfma_f32_16x16x32_bf16 v[102:105], v[158:161], v[210:213], v[102:105]
	v_mfma_f32_16x16x32_bf16 v[102:105], v[162:165], v[214:217], v[102:105]
	v_mfma_f32_16x16x32_bf16 v[94:97], v[174:177], v[214:217], v[94:97]
	v_mfma_f32_16x16x32_bf16 v[94:97], v[166:169], v[210:213], v[94:97]
	v_mfma_f32_16x16x32_bf16 v[82:85], v[178:181], v[210:213], v[82:85]
	v_mfma_f32_16x16x32_bf16 v[82:85], v[182:185], v[214:217], v[82:85]
	v_mfma_f32_16x16x32_bf16 v[74:77], v[190:193], v[214:217], v[74:77]
	v_mfma_f32_16x16x32_bf16 v[74:77], v[186:189], v[210:213], v[74:77]
	v_mfma_f32_16x16x32_bf16 v[66:69], v[186:189], v[218:221], v[66:69]
	v_mfma_f32_16x16x32_bf16 v[66:69], v[190:193], v[222:225], v[66:69]
	v_mfma_f32_16x16x32_bf16 v[70:73], v[182:185], v[222:225], v[70:73]
	v_mfma_f32_16x16x32_bf16 v[70:73], v[178:181], v[218:221], v[70:73]
	v_mfma_f32_16x16x32_bf16 v[78:81], v[166:169], v[218:221], v[78:81]
	v_mfma_f32_16x16x32_bf16 v[78:81], v[174:177], v[222:225], v[78:81]
	v_mfma_f32_16x16x32_bf16 v[86:89], v[162:165], v[222:225], v[86:89]
	v_mfma_f32_16x16x32_bf16 v[86:89], v[158:161], v[218:221], v[86:89]
	v_mfma_f32_16x16x32_bf16 v[62:65], v[158:161], v[226:229], v[62:65]
	v_mfma_f32_16x16x32_bf16 v[62:65], v[162:165], v[230:233], v[62:65]
	v_mfma_f32_16x16x32_bf16 v[58:61], v[174:177], v[230:233], v[58:61]
	v_mfma_f32_16x16x32_bf16 v[58:61], v[166:169], v[226:229], v[58:61]
	v_mfma_f32_16x16x32_bf16 v[50:53], v[178:181], v[226:229], v[50:53]
	v_mfma_f32_16x16x32_bf16 v[50:53], v[182:185], v[230:233], v[50:53]
	v_mfma_f32_16x16x32_bf16 v[42:45], v[190:193], v[230:233], v[42:45]
	v_mfma_f32_16x16x32_bf16 v[42:45], v[186:189], v[226:229], v[42:45]
	v_mfma_f32_16x16x32_bf16 v[26:29], v[186:189], v[234:237], v[26:29]
	v_mfma_f32_16x16x32_bf16 v[26:29], v[190:193], v[238:241], v[26:29]
	v_mfma_f32_16x16x32_bf16 v[34:37], v[182:185], v[238:241], v[34:37]
	v_mfma_f32_16x16x32_bf16 v[34:37], v[178:181], v[234:237], v[34:37]
	v_mfma_f32_16x16x32_bf16 v[46:49], v[166:169], v[234:237], v[46:49]
	v_mfma_f32_16x16x32_bf16 v[46:49], v[174:177], v[238:241], v[46:49]
	v_mfma_f32_16x16x32_bf16 v[54:57], v[162:165], v[238:241], v[54:57]
	v_mfma_f32_16x16x32_bf16 v[54:57], v[158:161], v[234:237], v[54:57]
	v_mfma_f32_16x16x32_bf16 v[38:41], v[158:161], v[242:245], v[38:41]
	v_mfma_f32_16x16x32_bf16 v[38:41], v[162:165], v[246:249], v[38:41]
	v_mfma_f32_16x16x32_bf16 v[30:33], v[174:177], v[246:249], v[30:33]
	v_mfma_f32_16x16x32_bf16 v[30:33], v[166:169], v[242:245], v[30:33]
	v_mfma_f32_16x16x32_bf16 v[18:21], v[178:181], v[242:245], v[18:21]
	v_mfma_f32_16x16x32_bf16 v[18:21], v[182:185], v[246:249], v[18:21]
	v_mfma_f32_16x16x32_bf16 v[10:13], v[190:193], v[246:249], v[10:13]
	v_mfma_f32_16x16x32_bf16 v[10:13], v[186:189], v[242:245], v[10:13]
	v_mfma_f32_16x16x32_bf16 v[2:5], v[186:189], v[250:253], v[2:5]
	v_mfma_f32_16x16x32_bf16 v[2:5], v[190:193], v[142:145], v[2:5]
	v_mfma_f32_16x16x32_bf16 v[6:9], v[182:185], v[142:145], v[6:9]
	v_mfma_f32_16x16x32_bf16 v[6:9], v[178:181], v[250:253], v[6:9]
	v_mfma_f32_16x16x32_bf16 v[14:17], v[166:169], v[250:253], v[14:17]
	v_mfma_f32_16x16x32_bf16 v[14:17], v[174:177], v[142:145], v[14:17]
	v_mfma_f32_16x16x32_bf16 v[22:25], v[162:165], v[142:145], v[22:25]
	v_mfma_f32_16x16x32_bf16 v[22:25], v[158:161], v[250:253], v[22:25]
	s_setprio 0
	s_waitcnt vmcnt(0)
	s_barrier
	s_add_i32 s57, s57, 1
	s_cmp_lt_u32 s57, 44
	s_cbranch_scc1 .Lp9k_B_loop
.Lp9k_done:
	v_mov_b64_e32 v[142:143], 0x200
	v_mov_b64_e32 v[144:145], 0x1ff
	s_and_b64 vcc, exec, s[14:15]
	s_cbranch_vccz .LBB0_951
	s_barrier
